# plus hand-written in-proj tile epilogue storing 128-byte row pieces (lane-pair half exchange)
# baseline (speedup 1.0000x reference)
; __device__ __forceinline__ int otid() { int t = threadIdx.x; asm volatile("" : "+v"(t)); return t; }
; #define PG8_STAGE(bufoff, gbase, voff) do { _Pragma("unroll") for (int _i = 0; _i < 2; ++_i) \
;         __builtin_amdgcn_global_load_lds((const unsigned*)((const char*)(gbase) + (voff)[_i]), (LAS unsigned*)(lds + (bufoff) + ldsw + _i * 8192), 16, 0, 0); } while (0)
; #define PG8_WAIT_V(n) asm volatile("s_waitcnt vmcnt(" #n ")" ::: "memory")
; template <class Epi, class Sched>
; __device__ __forceinline__ void gemm_phase(LAS unsigned char* lds, const Gemm g, const Sched& S, const Epi& E) {
;     const int tid = otid(), wid = __builtin_amdgcn_readfirstlane(tid >> 6), lane = tid & 63, wr = wid >> 2, wc = wid & 3, fr = lane & 15, fq = lane >> 4;
;     const int K = g.K, nt = K / BK, lda = g.lda;
;     unsigned voffA[2], voffB[2];
; #pragma unroll
;     for (int i = 0; i < 2; ++i) { int R, C; stage_rc(tid * 16 + i * 8192, R, C); const int Rb = Epi::PERM ? ((R & ~31) + perm32(R & 31)) : R;
;         voffA[i] = (unsigned)(R * lda + C) * 2u; voffB[i] = (unsigned)(Rb * K + C) * 2u; }
;     const size_t kstep = (size_t)(BK * 2);
;     const size_t hstepA = (size_t)HALF * lda * 2, hstepB = (size_t)HALF * K * 2;
;     const size_t tstepA = 2 * hstepA, tstepB = 2 * hstepB;
;     const unsigned ldsw = (unsigned)wid * 1024u;
;     const int aoff = lds_byte(wr * 64 + fr, fq * 8), boff = lds_byte(wc * 32 + fr, fq * 8);
;     ...
;     Unit cur, nxt; int ui = 0;
;     if (!S.next(0, cur)) return;
;     f32x4 acc[2][2][4][2];
; #pragma unroll
;     for (int a = 0; a < 2; ++a)
; #pragma unroll
;         for (int b = 0; b < 2; ++b)
; #pragma unroll
;             for (int m = 0; m < 4; ++m)
; #pragma unroll
;                 for (int n = 0; n < 2; ++n) acc[a][b][m][n] = (f32x4){0.f, 0.f, 0.f, 0.f};
;     bf16x8 At[4][2], B0[2][2], B1[2][2];
;     const char* cA = (const char*)g.A + (size_t)cur.pm * tstepA; const char* cB = (const char*)g.Bt + (size_t)cur.pn * tstepB;
;     PG8_STAGE(PG8_SB(0, 0), cB, voffB); PG8_STAGE(PG8_SB(0, 1), cB + hstepB, voffB); PG8_STAGE(PG8_SA(0, 0), cA, voffA); PG8_STAGE(PG8_SA(0, 1), cA + hstepA, voffA);
;     if (wr == 1) PG8_BAR;
;     PG8_WAIT_V(2); PG8_BAR;
;     PG8_STAGE(PG8_SB(1, 0), cB + kstep, voffB); PG8_STAGE(PG8_SA(1, 0), cA + kstep, voffA); PG8_STAGE(PG8_SB(1, 1), cB + hstepB + kstep, voffB);
;     PG8_WAIT_V(6); PG8_BAR;
.LBB0_255:
	v_and_b32_e32 v160, 15, v10
	v_lshrrev_b32_e32 v10, 1, v10
	v_readlane_b32 s18, v244, 31
	v_and_b32_e32 v161, 24, v10
	s_lshl_b32 s16, s16, 5
	v_mov_b32_e32 v135, v145
	v_readlane_b32 s19, v244, 32
	v_lshlrev_b32_e32 v10, 1, v161
	v_lshlrev_b32_e32 v11, 2, v160
	s_and_b32 s36, s16, 0x60
	s_add_i32 m0, s8, 0x18000
	v_lshl_add_u64 v[0:1], v[0:1], 0, s[0:1]
	v_lshl_add_u64 v[12:13], s[18:19], 0, v[134:135]
	v_mov_b32_e32 v131, v145
	s_lshl_b32 s35, s5, 6
	v_lshl_or_b32 v10, v160, 6, v10
	s_lshl_b32 s17, s5, 13
	v_and_b32_e32 v16, 32, v11
	s_lshl_b32 s16, s36, 8
	s_waitcnt vmcnt(2)
	s_barrier
	global_load_lds_dwordx4 v[0:1], off
	v_lshl_add_u64 v[0:1], v[2:3], 0, s[0:1]
	s_add_i32 m0, s8, 0x1a000
	s_add_i32 s37, s8, 0x8000
	s_add_i32 s38, s8, 0xa000
	v_lshl_add_u64 v[14:15], s[18:19], 0, v[130:131]
	v_bitop3_b32 v162, v10, s16, v16 bitop3:0xde
	global_load_lds_dwordx4 v[0:1], off
	v_lshl_add_u64 v[0:1], v[12:13], 0, s[0:1]
	s_mov_b32 m0, s37
	s_add_u32 s16, s14, 0x40080
	v_bitop3_b32 v17, v10, s17, v16 bitop3:0xde
	global_load_lds_dwordx4 v[0:1], off
	v_lshl_add_u64 v[0:1], v[14:15], 0, s[0:1]
	s_mov_b32 m0, s38
	s_addc_u32 s17, s15, 0
	global_load_lds_dwordx4 v[0:1], off
	s_add_i32 m0, s8, 0x1c000
	v_lshl_add_u64 v[0:1], s[16:17], 0, v[132:133]
	global_load_lds_dwordx4 v[0:1], off
	v_lshl_add_u64 v[0:1], s[16:17], 0, v[128:129]
	s_add_i32 m0, s8, 0x1e000
	s_cmpk_lt_u32 s4, 0x100
	global_load_lds_dwordx4 v[0:1], off
	v_lshlrev_b32_e32 v0, 14, v8
	v_and_b32_e32 v0, 0xffff8000, v0
	v_lshl_add_u32 v0, v7, 11, v0
	v_and_b32_e32 v1, 1, v8
	v_lshl_or_b32 v0, v1, 6, v0
	v_lshl_add_u32 v136, v9, 1, v0
	v_lshlrev_b32_e32 v0, 14, v4
	s_cselect_b64 s[50:51], -1, 0
	s_lshl_b32 s4, s5, 8
	v_and_b32_e32 v0, 0xffff8000, v0
	s_waitcnt vmcnt(6)
	s_add_i32 s4, s4, 0
	v_lshl_add_u32 v0, v5, 11, v0
	v_and_b32_e32 v1, 1, v4
	v_readlane_b32 s16, v244, 27
	s_add_i32 s4, s4, 0x20000
	v_lshl_or_b32 v0, v1, 6, v0
	v_readlane_b32 s17, v244, 28
	v_add_u32_e32 v163, s4, v11
	v_mov_b32_e32 v137, v145
	v_lshl_add_u32 v138, v6, 1, v0
	v_mov_b32_e32 v139, v145
	s_mov_b32 s4, 0
	v_add_u32_e32 v164, 0, v17
	v_readlane_b32 s39, v244, 10
	s_mov_b32 s5, s16
	s_mov_b64 s[16:17], s[18:19]
	s_barrier
	s_waitcnt vmcnt(0)
	s_branch .LBB0_258

; #define PG8_STAGE(bufoff, gbase, voff) do { _Pragma("unroll") for (int _i = 0; _i < 2; ++_i) \
;         __builtin_amdgcn_global_load_lds((const unsigned*)((const char*)(gbase) + (voff)[_i]), (LAS unsigned*)(lds + (bufoff) + ldsw + _i * 8192), 16, 0, 0); } while (0)
; #define PG8_LDA(dst, b, h) do { _Pragma("unroll") for (int m = 0; m < 4; ++m) _Pragma("unroll") for (int k = 0; k < 2; ++k) dst[m][k] = *(const LAS bf16x8*)(lds + PG8_SA(b, h) + aoff + m * 2048 + k * 1024); } while (0)
; #define PG8_LDB(dst, b, h) do { _Pragma("unroll") for (int n = 0; n < 2; ++n) _Pragma("unroll") for (int k = 0; k < 2; ++k) dst[n][k] = *(const LAS bf16x8*)(lds + PG8_SB(b, h) + boff + n * 2048 + k * 1024); } while (0)
; #define PG8_MMA(ai, bj, At, Bt) do { __builtin_amdgcn_s_setprio(1); _Pragma("unroll") for (int m = 0; m < 4; ++m) _Pragma("unroll") for (int n = 0; n < 2; ++n) _Pragma("unroll") for (int k = 0; k < 2; ++k) \
;         acc[ai][bj][m][n] = __builtin_amdgcn_mfma_f32_16x16x32_bf16(Bt[n][k], At[m][k], acc[ai][bj][m][n], 0, 0, 0); __builtin_amdgcn_s_setprio(0); } while (0)
; #define PG8_WAIT_V(n) asm volatile("s_waitcnt vmcnt(" #n ")" ::: "memory")
; #define PG8_WAIT_L(n) asm volatile("s_waitcnt lgkmcnt(" #n ")" ::: "memory")
; #define PG8_BAR __builtin_amdgcn_s_barrier()
; #define PG8_SCHED __builtin_amdgcn_sched_barrier(0)
; template <class Epi, class Sched>
; __device__ __forceinline__ void gemm_phase(LAS unsigned char* lds, const Gemm g, const Sched& S, const Epi& E) {
;     ...
;         for (int t = 0; t < nt; t += 2) {
;             const bool last = (t == nt - 2);
;             const char* a1 = cA + (size_t)(t + 1) * kstep;
;             const char* a2 = last ? nA : cA + (size_t)(t + 2) * kstep; const char* b2 = last ? nB : cB + (size_t)(t + 2) * kstep;
;             const char* a3 = a2 + kstep; const char* b3 = b2 + kstep;
;             PG8_LDB(B0, 0, 0); PG8_LDB(B1, 0, 1); PG8_SCHED; PG8_LDA(At, 0, 0); PG8_STAGE(PG8_SA(1, 1), a1 + hstepA, voffA);
;             PG8_WAIT_V(8); PG8_WAIT_L(0); PG8_BAR; PG8_MMA(0, 0, At, B0); PG8_MMA(0, 1, At, B1); PG8_BAR; PG8_SCHED;
;             PG8_LDA(At, 0, 1); PG8_STAGE(PG8_SB(0, 0), b2, voffB); PG8_STAGE(PG8_SB(0, 1), b2 + hstepB, voffB); PG8_STAGE(PG8_SA(0, 0), a2, voffA);
;             PG8_WAIT_V(8); PG8_WAIT_L(0); PG8_BAR; PG8_MMA(1, 0, At, B0); PG8_MMA(1, 1, At, B1); PG8_BAR; PG8_SCHED;
.LBB0_261:
	s_add_u32 s14, s42, 0xfffc0080
	s_addc_u32 s15, s43, -1
	s_add_i32 s63, 0, 0x10000
	s_cmp_eq_u32 s62, 12
	s_cselect_b32 s17, s18, s15
	s_cselect_b32 s16, s19, s14
	v_add_u32_e32 v144, s63, v162
	s_cselect_b32 s15, s53, s61
	s_cselect_b32 s14, s55, s60
	s_add_i32 s71, 0, 0x14000
	ds_read_b128 v[140:143], v144
	ds_read_b128 v[156:159], v144 offset:1024
	ds_read_b128 v[166:169], v144 offset:2048
	ds_read_b128 v[170:173], v144 offset:3072
	v_add_u32_e32 v144, 0x11000, v162
	ds_read_b128 v[174:177], v144
	ds_read_b128 v[180:183], v144 offset:1024
	ds_read_b128 v[192:195], v144 offset:2048
	ds_read_b128 v[196:199], v144 offset:3072
	v_lshl_add_u64 v[232:233], s[42:43], 0, v[136:137]
	s_add_i32 m0, s8, 0xc000
	ds_read_b128 v[200:203], v164
	ds_read_b128 v[204:207], v164 offset:1024
	ds_read_b128 v[208:211], v164 offset:2048
	ds_read_b128 v[212:215], v164 offset:3072
	ds_read_b128 v[216:219], v164 offset:4096
	ds_read_b128 v[220:223], v164 offset:5120
	ds_read_b128 v[224:227], v164 offset:6144
	ds_read_b128 v[228:231], v164 offset:7168
	global_load_lds_dwordx4 v[232:233], off
	v_lshl_add_u64 v[232:233], s[42:43], 0, v[138:139]
	s_add_i32 m0, s8, 0xe000
	s_nop 0
	global_load_lds_dwordx4 v[232:233], off
	s_waitcnt vmcnt(8)
	s_waitcnt lgkmcnt(0)
	s_barrier
	s_setprio 1
	s_waitcnt lgkmcnt(0)
	v_mfma_f32_16x16x32_bf16 v[124:127], v[140:143], v[200:203], v[124:127]
	v_mfma_f32_16x16x32_bf16 v[120:123], v[166:169], v[200:203], v[120:123]
	v_mfma_f32_16x16x32_bf16 v[108:111], v[140:143], v[208:211], v[108:111]
	v_mfma_f32_16x16x32_bf16 v[104:107], v[166:169], v[208:211], v[104:107]
	v_mfma_f32_16x16x32_bf16 v[92:95], v[140:143], v[216:219], v[92:95]
	v_mfma_f32_16x16x32_bf16 v[88:91], v[166:169], v[216:219], v[88:91]
	v_mfma_f32_16x16x32_bf16 v[76:79], v[140:143], v[224:227], v[76:79]
	v_mfma_f32_16x16x32_bf16 v[72:75], v[166:169], v[224:227], v[72:75]
	v_mfma_f32_16x16x32_bf16 v[124:127], v[156:159], v[204:207], v[124:127]
	v_mfma_f32_16x16x32_bf16 v[120:123], v[170:173], v[204:207], v[120:123]
	v_mfma_f32_16x16x32_bf16 v[108:111], v[156:159], v[212:215], v[108:111]
	v_mfma_f32_16x16x32_bf16 v[104:107], v[170:173], v[212:215], v[104:107]
	v_mfma_f32_16x16x32_bf16 v[92:95], v[156:159], v[220:223], v[92:95]
	v_mfma_f32_16x16x32_bf16 v[88:91], v[170:173], v[220:223], v[88:91]
	v_mfma_f32_16x16x32_bf16 v[76:79], v[156:159], v[228:231], v[76:79]
	v_mfma_f32_16x16x32_bf16 v[72:75], v[170:173], v[228:231], v[72:75]
	s_setprio 0
	s_setprio 1
	v_mfma_f32_16x16x32_bf16 v[116:119], v[174:177], v[200:203], v[116:119]
	v_mfma_f32_16x16x32_bf16 v[112:115], v[192:195], v[200:203], v[112:115]
	v_mfma_f32_16x16x32_bf16 v[100:103], v[174:177], v[208:211], v[100:103]
	v_mfma_f32_16x16x32_bf16 v[96:99], v[192:195], v[208:211], v[96:99]
	v_mfma_f32_16x16x32_bf16 v[84:87], v[174:177], v[216:219], v[84:87]
	v_mfma_f32_16x16x32_bf16 v[80:83], v[192:195], v[216:219], v[80:83]
	v_mfma_f32_16x16x32_bf16 v[68:71], v[174:177], v[224:227], v[68:71]
	v_mfma_f32_16x16x32_bf16 v[64:67], v[192:195], v[224:227], v[64:67]
	v_mfma_f32_16x16x32_bf16 v[116:119], v[180:183], v[204:207], v[116:119]
	v_mfma_f32_16x16x32_bf16 v[112:115], v[196:199], v[204:207], v[112:115]
	v_mfma_f32_16x16x32_bf16 v[100:103], v[180:183], v[212:215], v[100:103]
	v_mfma_f32_16x16x32_bf16 v[96:99], v[196:199], v[212:215], v[96:99]
	v_mfma_f32_16x16x32_bf16 v[84:87], v[180:183], v[220:223], v[84:87]
	v_mfma_f32_16x16x32_bf16 v[80:83], v[196:199], v[220:223], v[80:83]
	v_mfma_f32_16x16x32_bf16 v[68:71], v[180:183], v[228:231], v[68:71]
	v_mfma_f32_16x16x32_bf16 v[64:67], v[196:199], v[228:231], v[64:67]
	s_setprio 0
	s_barrier
	s_add_i32 s63, s63, s6
	v_lshl_add_u64 v[232:233], s[14:15], 0, v[132:133]
	s_mov_b32 m0, s63
	ds_read_b128 v[200:203], v164 offset:16384
	ds_read_b128 v[204:207], v164 offset:17408
	ds_read_b128 v[208:211], v164 offset:18432
	ds_read_b128 v[212:215], v164 offset:19456
	ds_read_b128 v[216:219], v164 offset:20480
	ds_read_b128 v[220:223], v164 offset:21504
	ds_read_b128 v[224:227], v164 offset:22528
	ds_read_b128 v[228:231], v164 offset:23552
	global_load_lds_dwordx4 v[232:233], off
	s_add_i32 m0, s63, 0x2000
	s_add_u32 s82, s14, 0x40000
	v_lshl_add_u64 v[234:235], s[14:15], 0, v[128:129]
	s_addc_u32 s83, s15, 0
	s_add_i32 s63, s71, s6
	global_load_lds_dwordx4 v[234:235], off
	v_lshl_add_u64 v[236:237], s[82:83], 0, v[132:133]
	s_mov_b32 m0, s63
	v_lshl_add_u64 v[238:239], s[16:17], 0, v[130:131]
	global_load_lds_dwordx4 v[236:237], off
	v_lshl_add_u64 v[236:237], s[82:83], 0, v[128:129]
	s_add_i32 m0, s63, 0x2000
	s_nop 0
	global_load_lds_dwordx4 v[236:237], off
	v_lshl_add_u64 v[236:237], s[16:17], 0, v[134:135]
	s_mov_b32 m0, s8
	s_nop 0
	global_load_lds_dwordx4 v[236:237], off
	s_mov_b32 m0, s9
	s_nop 0
	global_load_lds_dwordx4 v[238:239], off
	s_waitcnt vmcnt(8)
	s_waitcnt lgkmcnt(0)
	s_barrier
; #define PG8_STAGE(bufoff, gbase, voff) do { _Pragma("unroll") for (int _i = 0; _i < 2; ++_i) \
;         __builtin_amdgcn_global_load_lds((const unsigned*)((const char*)(gbase) + (voff)[_i]), (LAS unsigned*)(lds + (bufoff) + ldsw + _i * 8192), 16, 0, 0); } while (0)
; #define PG8_LDA(dst, b, h) do { _Pragma("unroll") for (int m = 0; m < 4; ++m) _Pragma("unroll") for (int k = 0; k < 2; ++k) dst[m][k] = *(const LAS bf16x8*)(lds + PG8_SA(b, h) + aoff + m * 2048 + k * 1024); } while (0)
; #define PG8_LDB(dst, b, h) do { _Pragma("unroll") for (int n = 0; n < 2; ++n) _Pragma("unroll") for (int k = 0; k < 2; ++k) dst[n][k] = *(const LAS bf16x8*)(lds + PG8_SB(b, h) + boff + n * 2048 + k * 1024); } while (0)
; #define PG8_MMA(ai, bj, At, Bt) do { __builtin_amdgcn_s_setprio(1); _Pragma("unroll") for (int m = 0; m < 4; ++m) _Pragma("unroll") for (int n = 0; n < 2; ++n) _Pragma("unroll") for (int k = 0; k < 2; ++k) \
;         acc[ai][bj][m][n] = __builtin_amdgcn_mfma_f32_16x16x32_bf16(Bt[n][k], At[m][k], acc[ai][bj][m][n], 0, 0, 0); __builtin_amdgcn_s_setprio(0); } while (0)
; #define PG8_WAIT_V(n) asm volatile("s_waitcnt vmcnt(" #n ")" ::: "memory")
; #define PG8_WAIT_L(n) asm volatile("s_waitcnt lgkmcnt(" #n ")" ::: "memory")
; #define PG8_BAR __builtin_amdgcn_s_barrier()
; #define PG8_SCHED __builtin_amdgcn_sched_barrier(0)
; template <class Epi, class Sched>
; __device__ __forceinline__ void gemm_phase(LAS unsigned char* lds, const Gemm g, const Sched& S, const Epi& E) {
;     ...
;             PG8_WAIT_V(8); PG8_WAIT_L(0); PG8_BAR; PG8_MMA(1, 0, At, B0); PG8_MMA(1, 1, At, B1); PG8_BAR; PG8_SCHED;
;             PG8_LDB(B0, 1, 0); PG8_LDB(B1, 1, 1); PG8_SCHED; PG8_LDA(At, 1, 0); PG8_STAGE(PG8_SA(0, 1), a2 + hstepA, voffA);
;             PG8_WAIT_V(8); PG8_WAIT_L(0); PG8_BAR; PG8_MMA(0, 0, At, B0); PG8_MMA(0, 1, At, B1); PG8_BAR; PG8_SCHED;
	s_setprio 1
	s_waitcnt lgkmcnt(0)
	v_mfma_f32_16x16x32_bf16 v[60:63], v[140:143], v[200:203], v[60:63]
	v_mfma_f32_16x16x32_bf16 v[56:59], v[166:169], v[200:203], v[56:59]
	v_mfma_f32_16x16x32_bf16 v[44:47], v[140:143], v[208:211], v[44:47]
	v_mfma_f32_16x16x32_bf16 v[40:43], v[166:169], v[208:211], v[40:43]
	v_mfma_f32_16x16x32_bf16 v[28:31], v[140:143], v[216:219], v[28:31]
	v_mfma_f32_16x16x32_bf16 v[24:27], v[166:169], v[216:219], v[24:27]
	v_mfma_f32_16x16x32_bf16 v[12:15], v[140:143], v[224:227], v[12:15]
	v_mfma_f32_16x16x32_bf16 v[8:11], v[166:169], v[224:227], v[8:11]
	v_mfma_f32_16x16x32_bf16 v[60:63], v[156:159], v[204:207], v[60:63]
	v_mfma_f32_16x16x32_bf16 v[56:59], v[170:173], v[204:207], v[56:59]
	v_mfma_f32_16x16x32_bf16 v[44:47], v[156:159], v[212:215], v[44:47]
	v_mfma_f32_16x16x32_bf16 v[40:43], v[170:173], v[212:215], v[40:43]
	v_mfma_f32_16x16x32_bf16 v[28:31], v[156:159], v[220:223], v[28:31]
	v_mfma_f32_16x16x32_bf16 v[24:27], v[170:173], v[220:223], v[24:27]
	v_mfma_f32_16x16x32_bf16 v[12:15], v[156:159], v[228:231], v[12:15]
	v_mfma_f32_16x16x32_bf16 v[8:11], v[170:173], v[228:231], v[8:11]
	s_setprio 0
	s_setprio 1
	v_mfma_f32_16x16x32_bf16 v[52:55], v[174:177], v[200:203], v[52:55]
	v_mfma_f32_16x16x32_bf16 v[48:51], v[192:195], v[200:203], v[48:51]
	v_mfma_f32_16x16x32_bf16 v[36:39], v[174:177], v[208:211], v[36:39]
	v_mfma_f32_16x16x32_bf16 v[32:35], v[192:195], v[208:211], v[32:35]
	v_mfma_f32_16x16x32_bf16 v[20:23], v[174:177], v[216:219], v[20:23]
	v_mfma_f32_16x16x32_bf16 v[16:19], v[192:195], v[216:219], v[16:19]
	v_mfma_f32_16x16x32_bf16 v[4:7], v[174:177], v[224:227], v[4:7]
	v_mfma_f32_16x16x32_bf16 v[0:3], v[192:195], v[224:227], v[0:3]
	v_mfma_f32_16x16x32_bf16 v[52:55], v[180:183], v[204:207], v[52:55]
	v_mfma_f32_16x16x32_bf16 v[48:51], v[196:199], v[204:207], v[48:51]
	v_mfma_f32_16x16x32_bf16 v[36:39], v[180:183], v[212:215], v[36:39]
	v_mfma_f32_16x16x32_bf16 v[32:35], v[196:199], v[212:215], v[32:35]
	v_mfma_f32_16x16x32_bf16 v[20:23], v[180:183], v[220:223], v[20:23]
	v_mfma_f32_16x16x32_bf16 v[16:19], v[196:199], v[220:223], v[16:19]
	v_mfma_f32_16x16x32_bf16 v[4:7], v[180:183], v[228:231], v[4:7]
	v_mfma_f32_16x16x32_bf16 v[0:3], v[196:199], v[228:231], v[0:3]
	s_setprio 0
	s_barrier
	s_add_i32 s63, 0, 0x18000
	v_add_u32_e32 v144, s63, v162
	s_add_i32 s71, 0, 0x1c000
	ds_read_b128 v[140:143], v144
	ds_read_b128 v[156:159], v144 offset:1024
	ds_read_b128 v[166:169], v144 offset:2048
	ds_read_b128 v[170:173], v144 offset:3072
	v_add_u32_e32 v144, 0x19000, v162
	ds_read_b128 v[174:177], v144
	ds_read_b128 v[180:183], v144 offset:1024
	ds_read_b128 v[192:195], v144 offset:2048
	ds_read_b128 v[196:199], v144 offset:3072
	s_add_u32 s16, s16, 0x40000
	s_addc_u32 s17, s17, 0
	s_mov_b32 m0, s10
	v_lshl_add_u64 v[240:241], s[16:17], 0, v[134:135]
	ds_read_b128 v[200:203], v164 offset:32768
	ds_read_b128 v[204:207], v164 offset:33792
	ds_read_b128 v[208:211], v164 offset:34816
	ds_read_b128 v[212:215], v164 offset:35840
	ds_read_b128 v[216:219], v164 offset:36864
	ds_read_b128 v[220:223], v164 offset:37888
	ds_read_b128 v[224:227], v164 offset:38912
	ds_read_b128 v[228:231], v164 offset:39936
	global_load_lds_dwordx4 v[240:241], off
	v_lshl_add_u64 v[240:241], s[16:17], 0, v[130:131]
	s_mov_b32 m0, s11
	s_nop 0
	global_load_lds_dwordx4 v[240:241], off
	s_waitcnt vmcnt(8)
	s_waitcnt lgkmcnt(0)
	s_barrier
	s_setprio 1
	s_waitcnt lgkmcnt(0)
	v_mfma_f32_16x16x32_bf16 v[124:127], v[140:143], v[200:203], v[124:127]
	v_mfma_f32_16x16x32_bf16 v[120:123], v[166:169], v[200:203], v[120:123]
	v_mfma_f32_16x16x32_bf16 v[108:111], v[140:143], v[208:211], v[108:111]
	v_mfma_f32_16x16x32_bf16 v[104:107], v[166:169], v[208:211], v[104:107]
	v_mfma_f32_16x16x32_bf16 v[92:95], v[140:143], v[216:219], v[92:95]
	v_mfma_f32_16x16x32_bf16 v[88:91], v[166:169], v[216:219], v[88:91]
	v_mfma_f32_16x16x32_bf16 v[76:79], v[140:143], v[224:227], v[76:79]
	v_mfma_f32_16x16x32_bf16 v[72:75], v[166:169], v[224:227], v[72:75]
	v_mfma_f32_16x16x32_bf16 v[124:127], v[156:159], v[204:207], v[124:127]
	v_mfma_f32_16x16x32_bf16 v[120:123], v[170:173], v[204:207], v[120:123]
	v_mfma_f32_16x16x32_bf16 v[108:111], v[156:159], v[212:215], v[108:111]
	v_mfma_f32_16x16x32_bf16 v[104:107], v[170:173], v[212:215], v[104:107]
	v_mfma_f32_16x16x32_bf16 v[92:95], v[156:159], v[220:223], v[92:95]
	v_mfma_f32_16x16x32_bf16 v[88:91], v[170:173], v[220:223], v[88:91]
	v_mfma_f32_16x16x32_bf16 v[76:79], v[156:159], v[228:231], v[76:79]
	v_mfma_f32_16x16x32_bf16 v[72:75], v[170:173], v[228:231], v[72:75]
	s_setprio 0
	s_setprio 1
	v_mfma_f32_16x16x32_bf16 v[116:119], v[174:177], v[200:203], v[116:119]
	v_mfma_f32_16x16x32_bf16 v[112:115], v[192:195], v[200:203], v[112:115]
	v_mfma_f32_16x16x32_bf16 v[100:103], v[174:177], v[208:211], v[100:103]
	v_mfma_f32_16x16x32_bf16 v[96:99], v[192:195], v[208:211], v[96:99]
	v_mfma_f32_16x16x32_bf16 v[84:87], v[174:177], v[216:219], v[84:87]
	v_mfma_f32_16x16x32_bf16 v[80:83], v[192:195], v[216:219], v[80:83]
	v_mfma_f32_16x16x32_bf16 v[68:71], v[174:177], v[224:227], v[68:71]
	v_mfma_f32_16x16x32_bf16 v[64:67], v[192:195], v[224:227], v[64:67]
	v_mfma_f32_16x16x32_bf16 v[116:119], v[180:183], v[204:207], v[116:119]
	v_mfma_f32_16x16x32_bf16 v[112:115], v[196:199], v[204:207], v[112:115]
	v_mfma_f32_16x16x32_bf16 v[100:103], v[180:183], v[212:215], v[100:103]
	v_mfma_f32_16x16x32_bf16 v[96:99], v[196:199], v[212:215], v[96:99]
	v_mfma_f32_16x16x32_bf16 v[84:87], v[180:183], v[220:223], v[84:87]
	v_mfma_f32_16x16x32_bf16 v[80:83], v[196:199], v[220:223], v[80:83]
	v_mfma_f32_16x16x32_bf16 v[68:71], v[180:183], v[228:231], v[68:71]
	v_mfma_f32_16x16x32_bf16 v[64:67], v[196:199], v[228:231], v[64:67]
	s_setprio 0
	s_barrier
;     __device__ __forceinline__ void operator()(const f32x4 (&acc)[2][2][4][2], const Unit& u, int wr, int wc, int fr, int fq, LAS unsigned char* lds) const {
;         const int row0 = u.pm * BM + wr * 64 + fr; const int col0 = u.pn * BM + wc * 32 + 8 * fq;
;         const LAS float* rtab = (const LAS float*)(lds + 131072);
;         const bool compact = u.pn >= 16;
; #pragma unroll
;         for (int ai = 0; ai < 2; ++ai)
; #pragma unroll
;             for (int m = 0; m < 4; ++m) { const int row = row0 + ai * HALF + m * 16;
;                 const float r = rtab[ai * HALF + wr * 64 + m * 16 + fr];
; #pragma unroll
;                 for (int bj = 0; bj < 2; ++bj) { const f32x4 v0 = acc[ai][bj][m][0] * r, v1 = acc[ai][bj][m][1] * r;
; template <class Epi, class Sched>
; __device__ __forceinline__ void gemm_phase(LAS unsigned char* lds, const Gemm g, const Sched& S, const Epi& E) {
;     ...
;         for (int t = 0; t < nt; t += 2) {
;             const bool last = (t == nt - 2);
;             const char* a1 = cA + (size_t)(t + 1) * kstep;
;             const char* a2 = last ? nA : cA + (size_t)(t + 2) * kstep; const char* b2 = last ? nB : cB + (size_t)(t + 2) * kstep;
;             const char* a3 = a2 + kstep; const char* b3 = b2 + kstep;
;             PG8_LDB(B0, 0, 0); PG8_LDB(B1, 0, 1); PG8_SCHED; PG8_LDA(At, 0, 0); PG8_STAGE(PG8_SA(1, 1), a1 + hstepA, voffA);
;             PG8_WAIT_V(8); PG8_WAIT_L(0); PG8_BAR; PG8_MMA(0, 0, At, B0); PG8_MMA(0, 1, At, B1); PG8_BAR; PG8_SCHED;
;             PG8_LDA(At, 0, 1); PG8_STAGE(PG8_SB(0, 0), b2, voffB); PG8_STAGE(PG8_SB(0, 1), b2 + hstepB, voffB); PG8_STAGE(PG8_SA(0, 0), a2, voffA);
;             PG8_WAIT_V(8); PG8_WAIT_L(0); PG8_BAR; PG8_MMA(1, 0, At, B0); PG8_MMA(1, 1, At, B1); PG8_BAR; PG8_SCHED;
;             PG8_LDB(B0, 1, 0); PG8_LDB(B1, 1, 1); PG8_SCHED; PG8_LDA(At, 1, 0); PG8_STAGE(PG8_SA(0, 1), a2 + hstepA, voffA);
;             PG8_WAIT_V(8); PG8_WAIT_L(0); PG8_BAR; PG8_MMA(0, 0, At, B0); PG8_MMA(0, 1, At, B1); PG8_BAR; PG8_SCHED;
;             PG8_LDA(At, 1, 1); PG8_STAGE(PG8_SB(1, 0), b3, voffB); PG8_STAGE(PG8_SB(1, 1), b3 + hstepB, voffB); PG8_STAGE(PG8_SA(1, 0), a3, voffA);
;             PG8_WAIT_V(8); PG8_WAIT_L(0); PG8_BAR; PG8_MMA(1, 0, At, B0); PG8_MMA(1, 1, At, B1); PG8_BAR; PG8_SCHED;
;         }
;         if (wr == 0) PG8_BAR;
;         E(acc, cur, wr, wc, fr, fq, lds);
	s_add_i32 s16, s63, s6
	v_lshl_add_u64 v[232:233], v[232:233], 0, s[0:1]
	s_mov_b32 m0, s16
	ds_read_b128 v[200:203], v164 offset:49152
	ds_read_b128 v[204:207], v164 offset:50176
	ds_read_b128 v[208:211], v164 offset:51200
	ds_read_b128 v[212:215], v164 offset:52224
	ds_read_b128 v[216:219], v164 offset:53248
	ds_read_b128 v[220:223], v164 offset:54272
	ds_read_b128 v[224:227], v164 offset:55296
	ds_read_b128 v[228:231], v164 offset:56320
	global_load_lds_dwordx4 v[232:233], off
	s_add_i32 m0, s16, 0x2000
	s_add_u32 s14, s14, 0x40080
	v_lshl_add_u64 v[232:233], v[234:235], 0, s[0:1]
	s_addc_u32 s15, s15, 0
	s_add_i32 s16, s71, s6
	global_load_lds_dwordx4 v[232:233], off
	v_lshl_add_u64 v[232:233], s[14:15], 0, v[132:133]
	s_mov_b32 m0, s16
	s_nop 0
	global_load_lds_dwordx4 v[232:233], off
	v_lshl_add_u64 v[232:233], s[14:15], 0, v[128:129]
	s_add_i32 m0, s16, 0x2000
	s_nop 0
	global_load_lds_dwordx4 v[232:233], off
	v_lshl_add_u64 v[232:233], v[236:237], 0, s[0:1]
	s_mov_b32 m0, s37
	s_nop 0
	global_load_lds_dwordx4 v[232:233], off
	v_lshl_add_u64 v[232:233], v[238:239], 0, s[0:1]
	s_mov_b32 m0, s38
	s_nop 0
	global_load_lds_dwordx4 v[232:233], off
	s_waitcnt vmcnt(8)
	s_waitcnt lgkmcnt(0)
	s_barrier
	s_setprio 1
	s_waitcnt lgkmcnt(0)
	v_mfma_f32_16x16x32_bf16 v[60:63], v[140:143], v[200:203], v[60:63]
	v_mfma_f32_16x16x32_bf16 v[56:59], v[166:169], v[200:203], v[56:59]
	v_mfma_f32_16x16x32_bf16 v[44:47], v[140:143], v[208:211], v[44:47]
	v_mfma_f32_16x16x32_bf16 v[40:43], v[166:169], v[208:211], v[40:43]
	v_mfma_f32_16x16x32_bf16 v[28:31], v[140:143], v[216:219], v[28:31]
	v_mfma_f32_16x16x32_bf16 v[24:27], v[166:169], v[216:219], v[24:27]
	v_mfma_f32_16x16x32_bf16 v[12:15], v[140:143], v[224:227], v[12:15]
	v_mfma_f32_16x16x32_bf16 v[8:11], v[166:169], v[224:227], v[8:11]
	v_mfma_f32_16x16x32_bf16 v[60:63], v[156:159], v[204:207], v[60:63]
	v_mfma_f32_16x16x32_bf16 v[56:59], v[170:173], v[204:207], v[56:59]
	v_mfma_f32_16x16x32_bf16 v[44:47], v[156:159], v[212:215], v[44:47]
	v_mfma_f32_16x16x32_bf16 v[40:43], v[170:173], v[212:215], v[40:43]
	v_mfma_f32_16x16x32_bf16 v[28:31], v[156:159], v[220:223], v[28:31]
	v_mfma_f32_16x16x32_bf16 v[24:27], v[170:173], v[220:223], v[24:27]
	v_mfma_f32_16x16x32_bf16 v[12:15], v[156:159], v[228:231], v[12:15]
	v_mfma_f32_16x16x32_bf16 v[8:11], v[170:173], v[228:231], v[8:11]
	s_setprio 0
	s_setprio 1
	v_mfma_f32_16x16x32_bf16 v[52:55], v[174:177], v[200:203], v[52:55]
	v_mfma_f32_16x16x32_bf16 v[48:51], v[192:195], v[200:203], v[48:51]
	v_mfma_f32_16x16x32_bf16 v[36:39], v[174:177], v[208:211], v[36:39]
	v_mfma_f32_16x16x32_bf16 v[32:35], v[192:195], v[208:211], v[32:35]
	v_mfma_f32_16x16x32_bf16 v[20:23], v[174:177], v[216:219], v[20:23]
	v_mfma_f32_16x16x32_bf16 v[16:19], v[192:195], v[216:219], v[16:19]
	v_mfma_f32_16x16x32_bf16 v[4:7], v[174:177], v[224:227], v[4:7]
	v_mfma_f32_16x16x32_bf16 v[0:3], v[192:195], v[224:227], v[0:3]
	v_mfma_f32_16x16x32_bf16 v[52:55], v[180:183], v[204:207], v[52:55]
	v_mfma_f32_16x16x32_bf16 v[48:51], v[196:199], v[204:207], v[48:51]
	v_mfma_f32_16x16x32_bf16 v[36:39], v[180:183], v[212:215], v[36:39]
	v_mfma_f32_16x16x32_bf16 v[32:35], v[196:199], v[212:215], v[32:35]
	v_mfma_f32_16x16x32_bf16 v[20:23], v[180:183], v[220:223], v[20:23]
	v_mfma_f32_16x16x32_bf16 v[16:19], v[196:199], v[220:223], v[16:19]
	v_mfma_f32_16x16x32_bf16 v[4:7], v[180:183], v[228:231], v[4:7]
	v_mfma_f32_16x16x32_bf16 v[0:3], v[196:199], v[228:231], v[0:3]
	s_setprio 0
	s_barrier
	s_add_i32 s62, s62, 2
	s_add_u32 s42, s42, 0x100
	s_addc_u32 s43, s43, 0
	s_add_u32 s60, s60, 0x100
	s_addc_u32 s61, s61, 0
	s_cmp_gt_u32 s62, 13
	s_cbranch_scc0 .LBB0_261
	s_and_b64 vcc, exec, s[50:51]
	s_cbranch_vccz .LBB0_264
	s_barrier
.LBB0_264:
	ds_read_b32 v170, v163
	ds_read_b32 v172, v163 offset:64
	ds_read_b32 v174, v163 offset:128
	ds_read_b32 v176, v163 offset:192
	ds_read_b32 v180, v163 offset:512
	ds_read_b32 v182, v163 offset:576
	ds_read_b32 v192, v163 offset:640
	ds_read_b32 v194, v163 offset:704
	s_lshl_b32 s18, s5, 8
	s_add_i32 s18, s18, s35
	v_and_b32_e32 v158, 7, v160
	v_lshrrev_b32_e32 v159, 3, v160
	v_add_u32_e32 v158, s18, v158
	v_lshlrev_b32_e32 v195, 1, v161
	v_lshl_add_u32 v195, v159, 6, v195
	v_mov_b32_e32 v159, 0
	s_cmp_lt_i32 s39, 16
	s_cbranch_scc0 .Lepi_in_compact
	v_lshlrev_b64 v[166:167], 13, v[158:159]
	v_lshl_add_u64 v[166:167], s[84:85], 0, v[166:167]
	s_lshl_b32 s16, s39, 9
	s_lshl_b32 s17, s36, 2
	s_add_i32 s16, s16, s17
	v_add_u32_e32 v158, s16, v195
	v_lshl_add_u64 v[166:167], v[166:167], 0, v[158:159]
	s_mov_b64 s[14:15], 0x10000
	s_mov_b64 s[16:17], 0x20000
	s_mov_b64 s[18:19], 0xa0000
	s_branch .Lepi_in_go
.Lepi_in_compact:
	s_and_b32 s16, s39, 0x7ffffe
	s_cmp_eq_u32 s16, 16
	s_cselect_b32 s17, s20, s22
	s_cselect_b32 s16, s33, s21
	s_lshr_b32 s14, s5, 3
	s_lshl_b32 s14, s14, 3
	s_and_b32 s15, s39, 1
	s_lshl_b32 s15, s15, 2
	s_or_b32 s14, s14, s15
	s_lshr_b32 s15, s36, 5
	s_or_b32 s14, s14, s15
	s_ashr_i32 s15, s14, 31
	s_lshl_b64 s[14:15], s[14:15], 18
	s_add_u32 s16, s16, s14
	s_addc_u32 s17, s17, s15
	v_and_b32_e32 v158, 0x7ff, v158
	v_lshl_add_u32 v158, v158, 7, v195
	v_lshl_add_u64 v[166:167], s[16:17], 0, v[158:159]
	s_mov_b64 s[14:15], 0x400
	s_mov_b64 s[16:17], 0x800
	s_mov_b64 s[18:19], 0x2800
; __device__ __forceinline__ unsigned cvt_pk_bf16(float lo, float hi) { unsigned r; asm volatile("v_cvt_pk_bf16_f32 %0, %1, %2" : "=v"(r) : "v"(lo), "v"(hi)); return r; }
;     __device__ __forceinline__ void operator()(const f32x4 (&acc)[2][2][4][2], const Unit& u, int wr, int wc, int fr, int fq, LAS unsigned char* lds) const {
;     ...
;             for (int m = 0; m < 4; ++m) { const int row = row0 + ai * HALF + m * 16;
;                 const float r = rtab[ai * HALF + wr * 64 + m * 16 + fr];
; #pragma unroll
;                 for (int bj = 0; bj < 2; ++bj) { const f32x4 v0 = acc[ai][bj][m][0] * r, v1 = acc[ai][bj][m][1] * r;
;                     u32x4 w; w.x = cvt_pk_bf16(v0[0], v0[1]); w.y = cvt_pk_bf16(v0[2], v0[3]); w.z = cvt_pk_bf16(v1[0], v1[1]); w.w = cvt_pk_bf16(v1[2], v1[3]);
;                     bf16_t* dst;
;                     if (compact) { const int cc = col0 + bj * HALF - 4096, hc = cc & 511, hh = hc >> 6, d = hc & 63;
;                         dst = ((cc >> 9) ? Vc : Kc) + ((size_t)((row >> 11) * 8 + hh) * 2048 + (row & 2047)) * 64 + d; }
;                     else dst = O + (size_t)row * ldc + col0 + bj * HALF;
;                     *(u32x4*)dst = w; } }
.Lepi_in_go:
	v_lshl_add_u64 v[168:169], v[166:167], 0, s[14:15]
	s_waitcnt lgkmcnt(7)
	v_pk_mul_f32 v[124:125], v[124:125], v[170:171] op_sel_hi:[1,0]
	v_pk_mul_f32 v[126:127], v[126:127], v[170:171] op_sel_hi:[1,0]
	v_pk_mul_f32 v[120:121], v[120:121], v[170:171] op_sel_hi:[1,0]
	v_pk_mul_f32 v[122:123], v[122:123], v[170:171] op_sel_hi:[1,0]
	v_pk_mul_f32 v[116:117], v[116:117], v[170:171] op_sel_hi:[1,0]
	v_pk_mul_f32 v[118:119], v[118:119], v[170:171] op_sel_hi:[1,0]
	v_pk_mul_f32 v[112:113], v[112:113], v[170:171] op_sel_hi:[1,0]
	v_pk_mul_f32 v[114:115], v[114:115], v[170:171] op_sel_hi:[1,0]
	v_cvt_pk_bf16_f32 v124, v124, v125
	v_cvt_pk_bf16_f32 v125, v126, v127
	v_cvt_pk_bf16_f32 v126, v120, v121
	v_cvt_pk_bf16_f32 v127, v122, v123
	v_cvt_pk_bf16_f32 v116, v116, v117
	v_cvt_pk_bf16_f32 v117, v118, v119
	v_cvt_pk_bf16_f32 v118, v112, v113
	v_cvt_pk_bf16_f32 v119, v114, v115
	v_mov_b32_dpp v156, v124 row_ror:8 row_mask:0xf bank_mask:0xf
	v_mov_b32_dpp v157, v125 row_ror:8 row_mask:0xf bank_mask:0xf
	v_mov_b32_dpp v124, v116 row_ror:8 row_mask:0xf bank_mask:0xc
	v_mov_b32_dpp v125, v117 row_ror:8 row_mask:0xf bank_mask:0xc
	v_mov_b32_dpp v116, v156 quad_perm:[0,1,2,3] row_mask:0xf bank_mask:0x3
	v_mov_b32_dpp v117, v157 quad_perm:[0,1,2,3] row_mask:0xf bank_mask:0x3
	v_mov_b32_dpp v156, v126 row_ror:8 row_mask:0xf bank_mask:0xf
	v_mov_b32_dpp v157, v127 row_ror:8 row_mask:0xf bank_mask:0xf
	v_mov_b32_dpp v126, v118 row_ror:8 row_mask:0xf bank_mask:0xc
	v_mov_b32_dpp v127, v119 row_ror:8 row_mask:0xf bank_mask:0xc
	v_mov_b32_dpp v118, v156 quad_perm:[0,1,2,3] row_mask:0xf bank_mask:0x3
	v_mov_b32_dpp v119, v157 quad_perm:[0,1,2,3] row_mask:0xf bank_mask:0x3
	global_store_dwordx4 v[166:167], v[124:127], off
	global_store_dwordx4 v[168:169], v[116:119], off
	v_lshl_add_u64 v[166:167], v[166:167], 0, s[16:17]
	v_lshl_add_u64 v[168:169], v[168:169], 0, s[16:17]
	s_waitcnt lgkmcnt(6)
	v_pk_mul_f32 v[108:109], v[108:109], v[172:173] op_sel_hi:[1,0]
	v_pk_mul_f32 v[110:111], v[110:111], v[172:173] op_sel_hi:[1,0]
	v_pk_mul_f32 v[104:105], v[104:105], v[172:173] op_sel_hi:[1,0]
	v_pk_mul_f32 v[106:107], v[106:107], v[172:173] op_sel_hi:[1,0]
	v_pk_mul_f32 v[100:101], v[100:101], v[172:173] op_sel_hi:[1,0]
	v_pk_mul_f32 v[102:103], v[102:103], v[172:173] op_sel_hi:[1,0]
	v_pk_mul_f32 v[96:97], v[96:97], v[172:173] op_sel_hi:[1,0]
	v_pk_mul_f32 v[98:99], v[98:99], v[172:173] op_sel_hi:[1,0]
	v_cvt_pk_bf16_f32 v108, v108, v109
	v_cvt_pk_bf16_f32 v109, v110, v111
	v_cvt_pk_bf16_f32 v110, v104, v105
	v_cvt_pk_bf16_f32 v111, v106, v107
	v_cvt_pk_bf16_f32 v100, v100, v101
	v_cvt_pk_bf16_f32 v101, v102, v103
	v_cvt_pk_bf16_f32 v102, v96, v97
	v_cvt_pk_bf16_f32 v103, v98, v99
	v_mov_b32_dpp v156, v108 row_ror:8 row_mask:0xf bank_mask:0xf
	v_mov_b32_dpp v157, v109 row_ror:8 row_mask:0xf bank_mask:0xf
	v_mov_b32_dpp v108, v100 row_ror:8 row_mask:0xf bank_mask:0xc
	v_mov_b32_dpp v109, v101 row_ror:8 row_mask:0xf bank_mask:0xc
	v_mov_b32_dpp v100, v156 quad_perm:[0,1,2,3] row_mask:0xf bank_mask:0x3
	v_mov_b32_dpp v101, v157 quad_perm:[0,1,2,3] row_mask:0xf bank_mask:0x3
	v_mov_b32_dpp v156, v110 row_ror:8 row_mask:0xf bank_mask:0xf
	v_mov_b32_dpp v157, v111 row_ror:8 row_mask:0xf bank_mask:0xf
	v_mov_b32_dpp v110, v102 row_ror:8 row_mask:0xf bank_mask:0xc
	v_mov_b32_dpp v111, v103 row_ror:8 row_mask:0xf bank_mask:0xc
	v_mov_b32_dpp v102, v156 quad_perm:[0,1,2,3] row_mask:0xf bank_mask:0x3
	v_mov_b32_dpp v103, v157 quad_perm:[0,1,2,3] row_mask:0xf bank_mask:0x3
	global_store_dwordx4 v[166:167], v[108:111], off
	global_store_dwordx4 v[168:169], v[100:103], off
	v_lshl_add_u64 v[166:167], v[166:167], 0, s[16:17]
	v_lshl_add_u64 v[168:169], v[168:169], 0, s[16:17]
	s_waitcnt lgkmcnt(5)
	v_pk_mul_f32 v[92:93], v[92:93], v[174:175] op_sel_hi:[1,0]
	v_pk_mul_f32 v[94:95], v[94:95], v[174:175] op_sel_hi:[1,0]
	v_pk_mul_f32 v[88:89], v[88:89], v[174:175] op_sel_hi:[1,0]
	v_pk_mul_f32 v[90:91], v[90:91], v[174:175] op_sel_hi:[1,0]
	v_pk_mul_f32 v[84:85], v[84:85], v[174:175] op_sel_hi:[1,0]
	v_pk_mul_f32 v[86:87], v[86:87], v[174:175] op_sel_hi:[1,0]
	v_pk_mul_f32 v[80:81], v[80:81], v[174:175] op_sel_hi:[1,0]
	v_pk_mul_f32 v[82:83], v[82:83], v[174:175] op_sel_hi:[1,0]
	v_cvt_pk_bf16_f32 v92, v92, v93
	v_cvt_pk_bf16_f32 v93, v94, v95
	v_cvt_pk_bf16_f32 v94, v88, v89
	v_cvt_pk_bf16_f32 v95, v90, v91
	v_cvt_pk_bf16_f32 v84, v84, v85
	v_cvt_pk_bf16_f32 v85, v86, v87
	v_cvt_pk_bf16_f32 v86, v80, v81
	v_cvt_pk_bf16_f32 v87, v82, v83
	v_mov_b32_dpp v156, v92 row_ror:8 row_mask:0xf bank_mask:0xf
	v_mov_b32_dpp v157, v93 row_ror:8 row_mask:0xf bank_mask:0xf
	v_mov_b32_dpp v92, v84 row_ror:8 row_mask:0xf bank_mask:0xc
	v_mov_b32_dpp v93, v85 row_ror:8 row_mask:0xf bank_mask:0xc
	v_mov_b32_dpp v84, v156 quad_perm:[0,1,2,3] row_mask:0xf bank_mask:0x3
	v_mov_b32_dpp v85, v157 quad_perm:[0,1,2,3] row_mask:0xf bank_mask:0x3
	v_mov_b32_dpp v156, v94 row_ror:8 row_mask:0xf bank_mask:0xf
	v_mov_b32_dpp v157, v95 row_ror:8 row_mask:0xf bank_mask:0xf
	v_mov_b32_dpp v94, v86 row_ror:8 row_mask:0xf bank_mask:0xc
	v_mov_b32_dpp v95, v87 row_ror:8 row_mask:0xf bank_mask:0xc
	v_mov_b32_dpp v86, v156 quad_perm:[0,1,2,3] row_mask:0xf bank_mask:0x3
	v_mov_b32_dpp v87, v157 quad_perm:[0,1,2,3] row_mask:0xf bank_mask:0x3
	global_store_dwordx4 v[166:167], v[92:95], off
	global_store_dwordx4 v[168:169], v[84:87], off
	v_lshl_add_u64 v[166:167], v[166:167], 0, s[16:17]
	v_lshl_add_u64 v[168:169], v[168:169], 0, s[16:17]
	s_waitcnt lgkmcnt(4)
; __device__ __forceinline__ unsigned cvt_pk_bf16(float lo, float hi) { unsigned r; asm volatile("v_cvt_pk_bf16_f32 %0, %1, %2" : "=v"(r) : "v"(lo), "v"(hi)); return r; }
;     __device__ __forceinline__ void operator()(const f32x4 (&acc)[2][2][4][2], const Unit& u, int wr, int wc, int fr, int fq, LAS unsigned char* lds) const {
;     ...
;             for (int m = 0; m < 4; ++m) { const int row = row0 + ai * HALF + m * 16;
;                 const float r = rtab[ai * HALF + wr * 64 + m * 16 + fr];
; #pragma unroll
;                 for (int bj = 0; bj < 2; ++bj) { const f32x4 v0 = acc[ai][bj][m][0] * r, v1 = acc[ai][bj][m][1] * r;
;                     u32x4 w; w.x = cvt_pk_bf16(v0[0], v0[1]); w.y = cvt_pk_bf16(v0[2], v0[3]); w.z = cvt_pk_bf16(v1[0], v1[1]); w.w = cvt_pk_bf16(v1[2], v1[3]);
;                     bf16_t* dst;
;                     if (compact) { const int cc = col0 + bj * HALF - 4096, hc = cc & 511, hh = hc >> 6, d = hc & 63;
;                         dst = ((cc >> 9) ? Vc : Kc) + ((size_t)((row >> 11) * 8 + hh) * 2048 + (row & 2047)) * 64 + d; }
;                     else dst = O + (size_t)row * ldc + col0 + bj * HALF;
;                     *(u32x4*)dst = w; } }
	v_pk_mul_f32 v[76:77], v[76:77], v[176:177] op_sel_hi:[1,0]
	v_pk_mul_f32 v[78:79], v[78:79], v[176:177] op_sel_hi:[1,0]
	v_pk_mul_f32 v[72:73], v[72:73], v[176:177] op_sel_hi:[1,0]
	v_pk_mul_f32 v[74:75], v[74:75], v[176:177] op_sel_hi:[1,0]
	v_pk_mul_f32 v[68:69], v[68:69], v[176:177] op_sel_hi:[1,0]
	v_pk_mul_f32 v[70:71], v[70:71], v[176:177] op_sel_hi:[1,0]
	v_pk_mul_f32 v[64:65], v[64:65], v[176:177] op_sel_hi:[1,0]
	v_pk_mul_f32 v[66:67], v[66:67], v[176:177] op_sel_hi:[1,0]
	v_cvt_pk_bf16_f32 v76, v76, v77
	v_cvt_pk_bf16_f32 v77, v78, v79
	v_cvt_pk_bf16_f32 v78, v72, v73
	v_cvt_pk_bf16_f32 v79, v74, v75
	v_cvt_pk_bf16_f32 v68, v68, v69
	v_cvt_pk_bf16_f32 v69, v70, v71
	v_cvt_pk_bf16_f32 v70, v64, v65
	v_cvt_pk_bf16_f32 v71, v66, v67
	v_mov_b32_dpp v156, v76 row_ror:8 row_mask:0xf bank_mask:0xf
	v_mov_b32_dpp v157, v77 row_ror:8 row_mask:0xf bank_mask:0xf
	v_mov_b32_dpp v76, v68 row_ror:8 row_mask:0xf bank_mask:0xc
	v_mov_b32_dpp v77, v69 row_ror:8 row_mask:0xf bank_mask:0xc
	v_mov_b32_dpp v68, v156 quad_perm:[0,1,2,3] row_mask:0xf bank_mask:0x3
	v_mov_b32_dpp v69, v157 quad_perm:[0,1,2,3] row_mask:0xf bank_mask:0x3
	v_mov_b32_dpp v156, v78 row_ror:8 row_mask:0xf bank_mask:0xf
	v_mov_b32_dpp v157, v79 row_ror:8 row_mask:0xf bank_mask:0xf
	v_mov_b32_dpp v78, v70 row_ror:8 row_mask:0xf bank_mask:0xc
	v_mov_b32_dpp v79, v71 row_ror:8 row_mask:0xf bank_mask:0xc
	v_mov_b32_dpp v70, v156 quad_perm:[0,1,2,3] row_mask:0xf bank_mask:0x3
	v_mov_b32_dpp v71, v157 quad_perm:[0,1,2,3] row_mask:0xf bank_mask:0x3
	global_store_dwordx4 v[166:167], v[76:79], off
	global_store_dwordx4 v[168:169], v[68:71], off
	v_lshl_add_u64 v[166:167], v[166:167], 0, s[18:19]
	v_lshl_add_u64 v[168:169], v[168:169], 0, s[18:19]
	s_waitcnt lgkmcnt(3)
	v_pk_mul_f32 v[60:61], v[60:61], v[180:181] op_sel_hi:[1,0]
	v_pk_mul_f32 v[62:63], v[62:63], v[180:181] op_sel_hi:[1,0]
	v_pk_mul_f32 v[56:57], v[56:57], v[180:181] op_sel_hi:[1,0]
	v_pk_mul_f32 v[58:59], v[58:59], v[180:181] op_sel_hi:[1,0]
	v_pk_mul_f32 v[52:53], v[52:53], v[180:181] op_sel_hi:[1,0]
	v_pk_mul_f32 v[54:55], v[54:55], v[180:181] op_sel_hi:[1,0]
	v_pk_mul_f32 v[48:49], v[48:49], v[180:181] op_sel_hi:[1,0]
	v_pk_mul_f32 v[50:51], v[50:51], v[180:181] op_sel_hi:[1,0]
	v_cvt_pk_bf16_f32 v60, v60, v61
	v_cvt_pk_bf16_f32 v61, v62, v63
	v_cvt_pk_bf16_f32 v62, v56, v57
	v_cvt_pk_bf16_f32 v63, v58, v59
	v_cvt_pk_bf16_f32 v52, v52, v53
	v_cvt_pk_bf16_f32 v53, v54, v55
	v_cvt_pk_bf16_f32 v54, v48, v49
	v_cvt_pk_bf16_f32 v55, v50, v51
	v_mov_b32_dpp v156, v60 row_ror:8 row_mask:0xf bank_mask:0xf
	v_mov_b32_dpp v157, v61 row_ror:8 row_mask:0xf bank_mask:0xf
	v_mov_b32_dpp v60, v52 row_ror:8 row_mask:0xf bank_mask:0xc
	v_mov_b32_dpp v61, v53 row_ror:8 row_mask:0xf bank_mask:0xc
	v_mov_b32_dpp v52, v156 quad_perm:[0,1,2,3] row_mask:0xf bank_mask:0x3
	v_mov_b32_dpp v53, v157 quad_perm:[0,1,2,3] row_mask:0xf bank_mask:0x3
	v_mov_b32_dpp v156, v62 row_ror:8 row_mask:0xf bank_mask:0xf
	v_mov_b32_dpp v157, v63 row_ror:8 row_mask:0xf bank_mask:0xf
	v_mov_b32_dpp v62, v54 row_ror:8 row_mask:0xf bank_mask:0xc
	v_mov_b32_dpp v63, v55 row_ror:8 row_mask:0xf bank_mask:0xc
	v_mov_b32_dpp v54, v156 quad_perm:[0,1,2,3] row_mask:0xf bank_mask:0x3
	v_mov_b32_dpp v55, v157 quad_perm:[0,1,2,3] row_mask:0xf bank_mask:0x3
	global_store_dwordx4 v[166:167], v[60:63], off
	global_store_dwordx4 v[168:169], v[52:55], off
	v_lshl_add_u64 v[166:167], v[166:167], 0, s[16:17]
	v_lshl_add_u64 v[168:169], v[168:169], 0, s[16:17]
	s_waitcnt lgkmcnt(2)
; __device__ __forceinline__ unsigned cvt_pk_bf16(float lo, float hi) { unsigned r; asm volatile("v_cvt_pk_bf16_f32 %0, %1, %2" : "=v"(r) : "v"(lo), "v"(hi)); return r; }
;     __device__ __forceinline__ void operator()(const f32x4 (&acc)[2][2][4][2], const Unit& u, int wr, int wc, int fr, int fq, LAS unsigned char* lds) const {
;     ...
;             for (int m = 0; m < 4; ++m) { const int row = row0 + ai * HALF + m * 16;
;                 const float r = rtab[ai * HALF + wr * 64 + m * 16 + fr];
; #pragma unroll
;                 for (int bj = 0; bj < 2; ++bj) { const f32x4 v0 = acc[ai][bj][m][0] * r, v1 = acc[ai][bj][m][1] * r;
;                     u32x4 w; w.x = cvt_pk_bf16(v0[0], v0[1]); w.y = cvt_pk_bf16(v0[2], v0[3]); w.z = cvt_pk_bf16(v1[0], v1[1]); w.w = cvt_pk_bf16(v1[2], v1[3]);
;                     bf16_t* dst;
;                     if (compact) { const int cc = col0 + bj * HALF - 4096, hc = cc & 511, hh = hc >> 6, d = hc & 63;
;                         dst = ((cc >> 9) ? Vc : Kc) + ((size_t)((row >> 11) * 8 + hh) * 2048 + (row & 2047)) * 64 + d; }
;                     else dst = O + (size_t)row * ldc + col0 + bj * HALF;
;                     *(u32x4*)dst = w; } }
	v_pk_mul_f32 v[44:45], v[44:45], v[182:183] op_sel_hi:[1,0]
	v_pk_mul_f32 v[46:47], v[46:47], v[182:183] op_sel_hi:[1,0]
	v_pk_mul_f32 v[40:41], v[40:41], v[182:183] op_sel_hi:[1,0]
	v_pk_mul_f32 v[42:43], v[42:43], v[182:183] op_sel_hi:[1,0]
	v_pk_mul_f32 v[36:37], v[36:37], v[182:183] op_sel_hi:[1,0]
	v_pk_mul_f32 v[38:39], v[38:39], v[182:183] op_sel_hi:[1,0]
	v_pk_mul_f32 v[32:33], v[32:33], v[182:183] op_sel_hi:[1,0]
	v_pk_mul_f32 v[34:35], v[34:35], v[182:183] op_sel_hi:[1,0]
	v_cvt_pk_bf16_f32 v44, v44, v45
	v_cvt_pk_bf16_f32 v45, v46, v47
	v_cvt_pk_bf16_f32 v46, v40, v41
	v_cvt_pk_bf16_f32 v47, v42, v43
	v_cvt_pk_bf16_f32 v36, v36, v37
	v_cvt_pk_bf16_f32 v37, v38, v39
	v_cvt_pk_bf16_f32 v38, v32, v33
	v_cvt_pk_bf16_f32 v39, v34, v35
	v_mov_b32_dpp v156, v44 row_ror:8 row_mask:0xf bank_mask:0xf
	v_mov_b32_dpp v157, v45 row_ror:8 row_mask:0xf bank_mask:0xf
	v_mov_b32_dpp v44, v36 row_ror:8 row_mask:0xf bank_mask:0xc
	v_mov_b32_dpp v45, v37 row_ror:8 row_mask:0xf bank_mask:0xc
	v_mov_b32_dpp v36, v156 quad_perm:[0,1,2,3] row_mask:0xf bank_mask:0x3
	v_mov_b32_dpp v37, v157 quad_perm:[0,1,2,3] row_mask:0xf bank_mask:0x3
	v_mov_b32_dpp v156, v46 row_ror:8 row_mask:0xf bank_mask:0xf
	v_mov_b32_dpp v157, v47 row_ror:8 row_mask:0xf bank_mask:0xf
	v_mov_b32_dpp v46, v38 row_ror:8 row_mask:0xf bank_mask:0xc
	v_mov_b32_dpp v47, v39 row_ror:8 row_mask:0xf bank_mask:0xc
	v_mov_b32_dpp v38, v156 quad_perm:[0,1,2,3] row_mask:0xf bank_mask:0x3
	v_mov_b32_dpp v39, v157 quad_perm:[0,1,2,3] row_mask:0xf bank_mask:0x3
	global_store_dwordx4 v[166:167], v[44:47], off
	global_store_dwordx4 v[168:169], v[36:39], off
	v_lshl_add_u64 v[166:167], v[166:167], 0, s[16:17]
	v_lshl_add_u64 v[168:169], v[168:169], 0, s[16:17]
	s_waitcnt lgkmcnt(1)
	v_pk_mul_f32 v[28:29], v[28:29], v[192:193] op_sel_hi:[1,0]
	v_pk_mul_f32 v[30:31], v[30:31], v[192:193] op_sel_hi:[1,0]
	v_pk_mul_f32 v[24:25], v[24:25], v[192:193] op_sel_hi:[1,0]
	v_pk_mul_f32 v[26:27], v[26:27], v[192:193] op_sel_hi:[1,0]
	v_pk_mul_f32 v[20:21], v[20:21], v[192:193] op_sel_hi:[1,0]
	v_pk_mul_f32 v[22:23], v[22:23], v[192:193] op_sel_hi:[1,0]
	v_pk_mul_f32 v[16:17], v[16:17], v[192:193] op_sel_hi:[1,0]
	v_pk_mul_f32 v[18:19], v[18:19], v[192:193] op_sel_hi:[1,0]
	v_cvt_pk_bf16_f32 v28, v28, v29
	v_cvt_pk_bf16_f32 v29, v30, v31
	v_cvt_pk_bf16_f32 v30, v24, v25
	v_cvt_pk_bf16_f32 v31, v26, v27
	v_cvt_pk_bf16_f32 v20, v20, v21
	v_cvt_pk_bf16_f32 v21, v22, v23
	v_cvt_pk_bf16_f32 v22, v16, v17
	v_cvt_pk_bf16_f32 v23, v18, v19
	v_mov_b32_dpp v156, v28 row_ror:8 row_mask:0xf bank_mask:0xf
	v_mov_b32_dpp v157, v29 row_ror:8 row_mask:0xf bank_mask:0xf
	v_mov_b32_dpp v28, v20 row_ror:8 row_mask:0xf bank_mask:0xc
	v_mov_b32_dpp v29, v21 row_ror:8 row_mask:0xf bank_mask:0xc
	v_mov_b32_dpp v20, v156 quad_perm:[0,1,2,3] row_mask:0xf bank_mask:0x3
	v_mov_b32_dpp v21, v157 quad_perm:[0,1,2,3] row_mask:0xf bank_mask:0x3
	v_mov_b32_dpp v156, v30 row_ror:8 row_mask:0xf bank_mask:0xf
	v_mov_b32_dpp v157, v31 row_ror:8 row_mask:0xf bank_mask:0xf
	v_mov_b32_dpp v30, v22 row_ror:8 row_mask:0xf bank_mask:0xc
	v_mov_b32_dpp v31, v23 row_ror:8 row_mask:0xf bank_mask:0xc
	v_mov_b32_dpp v22, v156 quad_perm:[0,1,2,3] row_mask:0xf bank_mask:0x3
	v_mov_b32_dpp v23, v157 quad_perm:[0,1,2,3] row_mask:0xf bank_mask:0x3
	global_store_dwordx4 v[166:167], v[28:31], off
	global_store_dwordx4 v[168:169], v[20:23], off
	v_lshl_add_u64 v[166:167], v[166:167], 0, s[16:17]
	v_lshl_add_u64 v[168:169], v[168:169], 0, s[16:17]
	s_waitcnt lgkmcnt(0)
	v_pk_mul_f32 v[12:13], v[12:13], v[194:195] op_sel_hi:[1,0]
	v_pk_mul_f32 v[14:15], v[14:15], v[194:195] op_sel_hi:[1,0]
	v_pk_mul_f32 v[8:9], v[8:9], v[194:195] op_sel_hi:[1,0]
	v_pk_mul_f32 v[10:11], v[10:11], v[194:195] op_sel_hi:[1,0]
	v_pk_mul_f32 v[4:5], v[4:5], v[194:195] op_sel_hi:[1,0]
	v_pk_mul_f32 v[6:7], v[6:7], v[194:195] op_sel_hi:[1,0]
	v_pk_mul_f32 v[0:1], v[0:1], v[194:195] op_sel_hi:[1,0]
	v_pk_mul_f32 v[2:3], v[2:3], v[194:195] op_sel_hi:[1,0]
	v_cvt_pk_bf16_f32 v12, v12, v13
	v_cvt_pk_bf16_f32 v13, v14, v15
	v_cvt_pk_bf16_f32 v14, v8, v9
	v_cvt_pk_bf16_f32 v15, v10, v11
	v_cvt_pk_bf16_f32 v4, v4, v5
	v_cvt_pk_bf16_f32 v5, v6, v7
	v_cvt_pk_bf16_f32 v6, v0, v1
	v_cvt_pk_bf16_f32 v7, v2, v3
	v_mov_b32_dpp v156, v12 row_ror:8 row_mask:0xf bank_mask:0xf
	v_mov_b32_dpp v157, v13 row_ror:8 row_mask:0xf bank_mask:0xf
	v_mov_b32_dpp v12, v4 row_ror:8 row_mask:0xf bank_mask:0xc
	v_mov_b32_dpp v13, v5 row_ror:8 row_mask:0xf bank_mask:0xc
	v_mov_b32_dpp v4, v156 quad_perm:[0,1,2,3] row_mask:0xf bank_mask:0x3
	v_mov_b32_dpp v5, v157 quad_perm:[0,1,2,3] row_mask:0xf bank_mask:0x3
	v_mov_b32_dpp v156, v14 row_ror:8 row_mask:0xf bank_mask:0xf
	v_mov_b32_dpp v157, v15 row_ror:8 row_mask:0xf bank_mask:0xf
	v_mov_b32_dpp v14, v6 row_ror:8 row_mask:0xf bank_mask:0xc
	v_mov_b32_dpp v15, v7 row_ror:8 row_mask:0xf bank_mask:0xc
	v_mov_b32_dpp v6, v156 quad_perm:[0,1,2,3] row_mask:0xf bank_mask:0x3
	v_mov_b32_dpp v7, v157 quad_perm:[0,1,2,3] row_mask:0xf bank_mask:0x3
	global_store_dwordx4 v[166:167], v[12:15], off
	global_store_dwordx4 v[168:169], v[4:7], off
	s_andn2_b64 vcc, exec, s[40:41]
	s_mov_b64 s[14:15], -1
	s_cbranch_vccnz .LBB0_257
	s_branch .LBB0_329
